# attention: speculative keys0-31 softmax (stale max) under QK block-1 MFMAs, block-major QK order, saddr DMA offsets
# speedup vs baseline: 1.0171x; 1.0020x over previous
; #define DMA_TILE(t, buf) do { const char* kt = (const char*)Kh + (size_t)(t) * (64 * 2048 * 2); const char* vt = (const char*)Vh + (size_t)(t) * (64 * 2048 * 2); \
;     _Pragma("unroll") for (int i = 0; i < 8; ++i) __builtin_amdgcn_global_load_lds((const unsigned*)((wid < 4 ? kt : vt) + src_off(wid * 8 + i, lane)), (LAS unsigned*)(lds + (buf) * 65536 + (wid * 8 + i) * 1024), 16, 0, 0); } while (0)
; __device__ __forceinline__ void dattn_unit(const bf16* __restrict__ Qb, const bf16* __restrict__ Kh, const bf16* __restrict__ Vh, int nq, int kv_lo, int kv_hi, int NT, ...
;     ...
;   const int tid = tid_, wid = __builtin_amdgcn_readfirstlane(tid >> 6), lane = tid & 63, r32 = lane & 31, hi = lane >> 5;
;   const int br = wid >> 2, rg = wid & 3;
;   const bool active = rg * 32 < nq;
;   const int kvalid = rg < 2 ? kv_lo : kv_hi;
;   float* wsf = (float*)(lds + 131072) + wid * 64; float* li_l = wsf; float* al_l = wsf + 32;
;   float m_reg = -1e30f, l_reg = 0; f32x16 o[8];
; #pragma unroll
;   for (int d = 0; d < 8; ++d) o[d] = f32x16{};
;   bf16x8 qr[8];
;   { const bf16* Qw = Qb + (long)(rg * 32 + r32) * 2048 + br * 128 + hi * 8;
; #pragma unroll
;     for (int d0 = 0; d0 < 8; ++d0) qr[d0] = *reinterpret_cast<const bf16x8*>(Qw + d0 * 16); }
;     ...
;   DMA_TILE(0, 0);
.LBB0_935:
	s_and_b32 s0, s21, 0x3fffffc0
	s_lshl_b32 s0, s0, 2
	s_add_i32 s0, s0, 0
	s_add_i32 s6, s0, 0x20000
	s_cmp_lt_u32 s2, 2
	s_cselect_b32 s25, s17, s16
	s_cmp_lt_u32 s80, s20
	s_cselect_b64 s[12:13], -1, 0
	s_add_i32 m0, s24, 0x1c00
	v_lshlrev_b32_e32 v28, 1, v233
	global_load_lds_dwordx4 v2, s[14:15]
	v_and_b32_e32 v28, 32, v28
	s_movk_i32 s16, 0xc0
	v_and_or_b32 v12, v12, s16, v28
	v_and_b32_e32 v9, 0x100, v9
	s_lshr_b32 s7, s19, 8
	v_or3_b32 v235, v12, v9, v7
	v_or_b32_e32 v12, s7, v5
	v_and_or_b32 v12, v12, 35, v6
	v_lshlrev_b32_e32 v12, 12, v12
	v_lshlrev_b32_e32 v8, 1, v8
	v_lshl_or_b32 v10, v10, 4, v11
	v_or3_b32 v11, v7, v13, s18
	s_lshr_b32 s7, s8, 8
	v_add_u32_e32 v28, v12, v8
	v_lshl_add_u32 v11, v11, 1, v12
	v_lshl_or_b32 v13, v14, 4, v15
	v_or_b32_e32 v12, 0x4000, v12
	v_lshl_or_b32 v15, v16, 4, v17
	v_or3_b32 v16, v7, v18, s18
	v_or_b32_e32 v17, s7, v5
	s_lshr_b32 s7, s9, 8
	v_add_u32_e32 v14, v12, v8
	v_lshl_add_u32 v12, v16, 1, v12
	v_lshl_or_b32 v16, v19, 4, v20
	v_or_b32_e32 v19, s7, v5
	s_lshr_b32 s7, s27, 8
	v_lshlrev_b32_e32 v4, 4, v4
	v_or_b32_e32 v5, s7, v5
	s_movk_i32 s7, 0x70
	v_and_b32_e32 v9, 0x70, v4
	v_bitop3_b32 v238, v0, v4, s7 bitop3:0x78
	s_movk_i32 s7, 0x60
	v_and_or_b32 v19, v19, 51, v6
	v_and_or_b32 v5, v5, 51, v6
	v_bitop3_b32 v241, v0, v9, s7 bitop3:0x36
	s_movk_i32 s7, 0x80
	v_and_or_b32 v17, v17, 51, v6
	v_or3_b32 v7, v7, v23, s18
	v_lshlrev_b32_e32 v19, 12, v19
	v_lshlrev_b32_e32 v5, 12, v5
	v_bitop3_b32 v242, v0, v9, s7 bitop3:0x36
	s_movk_i32 s7, 0xa0
	v_lshl_add_u32 v17, v17, 12, v8
	v_lshl_or_b32 v18, v21, 4, v22
	v_lshl_add_u32 v19, v7, 1, v19
	v_lshl_or_b32 v20, v24, 4, v25
	v_add3_u32 v21, v8, v5, s91
	v_lshl_or_b32 v22, v26, 4, v27
	v_bitop3_b32 v243, v0, v9, s7 bitop3:0x36
	s_movk_i32 s7, 0xe0
	v_bitop3_b32 v239, v0, v9, 32 bitop3:0x36
	v_bitop3_b32 v240, v0, v9, 64 bitop3:0x36
	v_bitop3_b32 v244, v0, v9, s16 bitop3:0x36
	v_bitop3_b32 v245, v0, v9, s7 bitop3:0x36
	v_add_u32_e32 v237, s6, v0
	v_cndmask_b32_e64 v0, v28, v10, s[4:5]
	v_cndmask_b32_e64 v4, v11, v13, s[4:5]
	v_cndmask_b32_e64 v6, v14, v15, s[4:5]
	v_cndmask_b32_e64 v8, v12, v16, s[4:5]
	v_cndmask_b32_e64 v10, v17, v18, s[4:5]
	v_cndmask_b32_e64 v12, v19, v20, s[4:5]
	v_cndmask_b32_e64 v14, v21, v22, s[4:5]
	v_mov_b32_e32 v15, v1
	s_mov_b64 s[4:5], 0x40000
	v_mov_b32_e32 v3, v1
	v_mov_b32_e32 v5, v1
	v_mov_b32_e32 v7, v1
	v_mov_b32_e32 v9, v1
	v_mov_b32_e32 v11, v1
	v_mov_b32_e32 v13, v1
	v_add_u32_e32 v218, 0x40000, v14
	v_mov_b32_e32 v14, v1
	v_add_u32_e32 v212, 0x40000, v0
	v_add_u32_e32 v213, 0x40000, v4
	v_add_u32_e32 v214, 0x40000, v6
	v_add_u32_e32 v215, 0x40000, v8
	v_add_u32_e32 v216, 0x40000, v10
	v_add_u32_e32 v217, 0x40000, v12
	v_add_u32_e32 v219, 0x40000, v2
	v_mov_b32_e32 v0, v1
	v_mov_b32_e32 v2, v1
	v_mov_b32_e32 v4, v1
	v_mov_b32_e32 v6, v1
	v_mov_b32_e32 v8, v1
	v_mov_b32_e32 v10, v1
	v_mov_b32_e32 v12, v1
	v_mov_b64_e32 v[128:129], v[14:15]
	v_mov_b64_e32 v[112:113], v[14:15]
	v_mov_b64_e32 v[96:97], v[14:15]
	v_mov_b64_e32 v[80:81], v[14:15]
	v_mov_b64_e32 v[64:65], v[14:15]
	v_mov_b64_e32 v[48:49], v[14:15]
	v_mov_b64_e32 v[32:33], v[14:15]
	v_mov_b64_e32 v[126:127], v[12:13]
	v_mov_b64_e32 v[124:125], v[10:11]
	v_mov_b64_e32 v[122:123], v[8:9]
	v_mov_b64_e32 v[120:121], v[6:7]
	v_mov_b64_e32 v[118:119], v[4:5]
	v_mov_b64_e32 v[116:117], v[2:3]
	v_mov_b64_e32 v[114:115], v[0:1]
	v_mov_b64_e32 v[110:111], v[12:13]
	v_mov_b64_e32 v[108:109], v[10:11]
	v_mov_b64_e32 v[106:107], v[8:9]
	v_mov_b64_e32 v[104:105], v[6:7]
	v_mov_b64_e32 v[102:103], v[4:5]
	v_mov_b64_e32 v[100:101], v[2:3]
	v_mov_b64_e32 v[98:99], v[0:1]
	v_mov_b64_e32 v[94:95], v[12:13]
	v_mov_b64_e32 v[92:93], v[10:11]
	v_mov_b64_e32 v[90:91], v[8:9]
	v_mov_b64_e32 v[88:89], v[6:7]
	v_mov_b64_e32 v[86:87], v[4:5]
	v_mov_b64_e32 v[84:85], v[2:3]
	v_mov_b64_e32 v[82:83], v[0:1]
	v_mov_b64_e32 v[78:79], v[12:13]
	v_mov_b64_e32 v[76:77], v[10:11]
	v_mov_b64_e32 v[74:75], v[8:9]
	v_mov_b64_e32 v[72:73], v[6:7]
	v_mov_b64_e32 v[70:71], v[4:5]
	v_mov_b64_e32 v[68:69], v[2:3]
	v_mov_b64_e32 v[66:67], v[0:1]
	v_mov_b64_e32 v[62:63], v[12:13]
	v_mov_b64_e32 v[60:61], v[10:11]
	v_mov_b64_e32 v[58:59], v[8:9]
	v_mov_b64_e32 v[56:57], v[6:7]
	v_mov_b64_e32 v[54:55], v[4:5]
	v_mov_b64_e32 v[52:53], v[2:3]
	v_mov_b64_e32 v[50:51], v[0:1]
	v_mov_b64_e32 v[46:47], v[12:13]
	v_mov_b64_e32 v[44:45], v[10:11]
	v_mov_b64_e32 v[42:43], v[8:9]
	v_mov_b64_e32 v[40:41], v[6:7]
	v_mov_b64_e32 v[38:39], v[4:5]
	v_mov_b64_e32 v[36:37], v[2:3]
	v_mov_b64_e32 v[34:35], v[0:1]
	v_mov_b64_e32 v[30:31], v[12:13]
	v_mov_b64_e32 v[28:29], v[10:11]
	v_mov_b64_e32 v[26:27], v[8:9]
	v_mov_b64_e32 v[24:25], v[6:7]
	v_mov_b64_e32 v[22:23], v[4:5]
	v_mov_b64_e32 v[20:21], v[2:3]
	v_mov_b64_e32 v[18:19], v[0:1]
	v_mov_b64_e32 v[16:17], v[14:15]
	s_lshl_b32 s26, s22, 14
	v_lshlrev_b32_e32 v236, 8, v230
	v_cmp_gt_u32_e64 s[0:1], 32, v233
	v_lshl_add_u32 v234, v230, 2, s6
	v_lshlrev_b32_e32 v232, 2, v231
	s_mov_b32 s27, 0
	v_mov_b32_e32 v247, 0
	v_mov_b32_e32 v246, 0xf149f2ca
	v_mov_b64_e32 v[14:15], v[12:13]
	v_mov_b64_e32 v[12:13], v[10:11]
	v_mov_b64_e32 v[10:11], v[8:9]
	v_mov_b64_e32 v[8:9], v[6:7]
	v_mov_b64_e32 v[6:7], v[4:5]
	v_mov_b64_e32 v[4:5], v[2:3]
	v_mov_b64_e32 v[2:3], v[0:1]
	s_mov_b32 s28, 0
	s_waitcnt vmcnt(0)
	s_branch .LBB0_939

; __device__ __forceinline__ int crow(int r, int hi) { return (r & 3) + 8 * (r >> 2) + 4 * hi; }
; #define SBAR() __builtin_amdgcn_sched_barrier(0)
; __device__ __forceinline__ void partialSM(f32x16& p0, f32x16& p1, float& m_reg, float& mn, float& alpha, int rem, int hi) {
;     ...
;   for (int r = 0; r < 16; ++r) p0[r] = fmaf(p0[r], C, mnC);
; #pragma unroll
;   for (int r = 0; r < 16; ++r) p1[r] = fmaf(p1[r], C, mnC);
; #pragma unroll
;   for (int r = 0; r < 16; ++r) p0[r] = __builtin_amdgcn_exp2f(p0[r]);
; }
; __device__ __forceinline__ void finishSM(f32x16& p0, f32x16& p1, float alpha, float& l_reg, bf16x8& pa0, bf16x8& pa1, bf16x8& pa2, bf16x8& pa3) {
; #pragma unroll
;   for (int r = 0; r < 16; ++r) p1[r] = __builtin_amdgcn_exp2f(p1[r]);
;   float ps = 0;
; #pragma unroll
;   for (int r = 0; r < 16; ++r) ps += p0[r];
; #pragma unroll
;   for (int r = 0; r < 16; ++r) ps += p1[r];
;   { auto rr = __builtin_amdgcn_permlane32_swap(__float_as_uint(ps), __float_as_uint(ps), false, false);
;     ps = __uint_as_float(rr[0]) + __uint_as_float(rr[1]); }
;   l_reg = l_reg * alpha + ps;
; __device__ __forceinline__ void dattn_unit(const bf16* __restrict__ Qb, const bf16* __restrict__ Kh, const bf16* __restrict__ Vh, int nq, int kv_lo, int kv_hi, int NT, ...
;     ...
;       partialSM(p0, p1, m_reg, mn, al, rem, hi);
;       if (__any(al < 1.f)) { if (hi == 0) al_l[r32] = al; asm volatile("s_waitcnt lgkmcnt(0)" ::: "memory");
; #pragma unroll
;         for (int d = 0; d < 8; ++d)
; #pragma unroll
;           for (int r = 0; r < 16; ++r) o[d][r] *= al_l[crow(r, hi)]; }
;       finishSM(p0, p1, al, l_reg, pa0, pa1, pa2, pa3); SBAR();
;       pv_one8<0>(o[0], vb, pa0, pa1, pa2, pa3); pv_one8<1>(o[1], vb, pa0, pa1, pa2, pa3); pv_one8<2>(o[2], vb, pa0, pa1, pa2, pa3); pv_one8<3>(o[3], vb, pa0, pa1, pa2, pa3);
;       pv_one8<4>(o[4], vb, pa0, pa1, pa2, pa3); pv_one8<5>(o[5], vb, pa0, pa1, pa2, pa3); pv_one8<6>(o[6], vb, pa0, pa1, pa2, pa3); pv_one8<7>(o[7], vb, pa0, pa1, pa2, pa3);
.LBB0_937:
	v_cndmask_b32_e64 v246, v248, v246, s[4:5]
	s_cmp_lg_u64 s[4:5], 0
	s_cbranch_scc0 .Latt_s1_redo
	s_cmp_gt_u32 s25, 63
	s_cbranch_scc0 .Latt_s1_redo
.Latt_pv:
	s_add_i32 s29, s29, 0x8000
	v_add_u32_e32 v195, s29, v235
	ds_read_b64_tr_b16 v[146:147], v195 offset:0
	ds_read_b64_tr_b16 v[148:149], v195 offset:2048
	ds_read_b64_tr_b16 v[150:151], v195 offset:4096
	ds_read_b64_tr_b16 v[152:153], v195 offset:6144
	ds_read_b64_tr_b16 v[154:155], v195 offset:512
	ds_read_b64_tr_b16 v[156:157], v195 offset:2560
	ds_read_b64_tr_b16 v[158:159], v195 offset:4608
	ds_read_b64_tr_b16 v[160:161], v195 offset:6656
	s_waitcnt lgkmcnt(4)
	v_mfma_f32_32x32x16_bf16 v[114:129], v[220:223], v[146:149], v[114:129]
	v_fmamk_f32 v130, v130, 0x3e0293ee, v249
	v_fmamk_f32 v131, v131, 0x3e0293ee, v249
	v_fmamk_f32 v132, v132, 0x3e0293ee, v249
	v_fmamk_f32 v133, v133, 0x3e0293ee, v249
	v_mfma_f32_32x32x16_bf16 v[114:129], v[224:227], v[150:153], v[114:129]
	v_fmamk_f32 v134, v134, 0x3e0293ee, v249
	v_fmamk_f32 v135, v135, 0x3e0293ee, v249
	v_fmamk_f32 v136, v136, 0x3e0293ee, v249
	v_fmamk_f32 v137, v137, 0x3e0293ee, v249
	ds_read_b64_tr_b16 v[146:147], v195 offset:1024
	ds_read_b64_tr_b16 v[148:149], v195 offset:3072
	ds_read_b64_tr_b16 v[150:151], v195 offset:5120
	ds_read_b64_tr_b16 v[152:153], v195 offset:7168
	s_waitcnt lgkmcnt(4)
	v_mfma_f32_32x32x16_bf16 v[98:113], v[220:223], v[154:157], v[98:113]
	v_fmamk_f32 v138, v138, 0x3e0293ee, v249
	v_fmamk_f32 v139, v139, 0x3e0293ee, v249
	v_fmamk_f32 v140, v140, 0x3e0293ee, v249
	v_fmamk_f32 v141, v141, 0x3e0293ee, v249
	v_mfma_f32_32x32x16_bf16 v[98:113], v[224:227], v[158:161], v[98:113]
	v_fmamk_f32 v142, v142, 0x3e0293ee, v249
	v_fmamk_f32 v143, v143, 0x3e0293ee, v249
	v_fmamk_f32 v144, v144, 0x3e0293ee, v249
	v_fmamk_f32 v145, v145, 0x3e0293ee, v249
	ds_read_b64_tr_b16 v[154:155], v195 offset:1536
	ds_read_b64_tr_b16 v[156:157], v195 offset:3584
	ds_read_b64_tr_b16 v[158:159], v195 offset:5632
	ds_read_b64_tr_b16 v[160:161], v195 offset:7680
	s_waitcnt lgkmcnt(4)
	v_mfma_f32_32x32x16_bf16 v[82:97], v[220:223], v[146:149], v[82:97]
	v_exp_f32_e32 v130, v130
	v_exp_f32_e32 v131, v131
	v_mfma_f32_32x32x16_bf16 v[82:97], v[224:227], v[150:153], v[82:97]
	v_exp_f32_e32 v132, v132
	v_exp_f32_e32 v133, v133
	v_add_f32_e32 v204, v130, v131
	ds_read_b64_tr_b16 v[146:147], v195 offset:16384
	ds_read_b64_tr_b16 v[148:149], v195 offset:18432
	ds_read_b64_tr_b16 v[150:151], v195 offset:20480
	ds_read_b64_tr_b16 v[152:153], v195 offset:22528
	s_waitcnt lgkmcnt(4)
	v_mfma_f32_32x32x16_bf16 v[66:81], v[220:223], v[154:157], v[66:81]
	v_exp_f32_e32 v134, v134
	v_exp_f32_e32 v135, v135
	v_add_f32_e32 v204, v132, v204
	v_add_f32_e32 v204, v133, v204
	v_mfma_f32_32x32x16_bf16 v[66:81], v[224:227], v[158:161], v[66:81]
	v_exp_f32_e32 v136, v136
	v_exp_f32_e32 v137, v137
	v_add_f32_e32 v204, v134, v204
	v_add_f32_e32 v204, v135, v204
	ds_read_b64_tr_b16 v[154:155], v195 offset:16896
	ds_read_b64_tr_b16 v[156:157], v195 offset:18944
	ds_read_b64_tr_b16 v[158:159], v195 offset:20992
	ds_read_b64_tr_b16 v[160:161], v195 offset:23040
	s_waitcnt lgkmcnt(4)
	v_mfma_f32_32x32x16_bf16 v[50:65], v[220:223], v[146:149], v[50:65]
	v_exp_f32_e32 v138, v138
	v_exp_f32_e32 v139, v139
	v_add_f32_e32 v204, v136, v204
	v_add_f32_e32 v204, v137, v204
	v_mfma_f32_32x32x16_bf16 v[50:65], v[224:227], v[150:153], v[50:65]
	v_exp_f32_e32 v140, v140
	v_exp_f32_e32 v141, v141
	v_add_f32_e32 v204, v138, v204
	v_add_f32_e32 v204, v139, v204
	v_cvt_pk_bf16_f32 v130, v130, v131
	ds_read_b64_tr_b16 v[146:147], v195 offset:17408
	ds_read_b64_tr_b16 v[148:149], v195 offset:19456
	ds_read_b64_tr_b16 v[150:151], v195 offset:21504
	ds_read_b64_tr_b16 v[152:153], v195 offset:23552
	s_waitcnt lgkmcnt(4)
	v_mfma_f32_32x32x16_bf16 v[34:49], v[220:223], v[154:157], v[34:49]
	v_exp_f32_e32 v142, v142
	v_exp_f32_e32 v143, v143
	v_add_f32_e32 v204, v140, v204
	v_add_f32_e32 v204, v141, v204
	v_cvt_pk_bf16_f32 v131, v132, v133
	v_mfma_f32_32x32x16_bf16 v[34:49], v[224:227], v[158:161], v[34:49]
	v_exp_f32_e32 v144, v144
	v_exp_f32_e32 v145, v145
	v_add_f32_e32 v204, v142, v204
	v_add_f32_e32 v204, v143, v204
	v_cvt_pk_bf16_f32 v132, v134, v135
	ds_read_b64_tr_b16 v[154:155], v195 offset:17920
	ds_read_b64_tr_b16 v[156:157], v195 offset:19968
	ds_read_b64_tr_b16 v[158:159], v195 offset:22016
	ds_read_b64_tr_b16 v[160:161], v195 offset:24064
	s_waitcnt lgkmcnt(4)
; __device__ __forceinline__ void finishSM(f32x16& p0, f32x16& p1, float alpha, float& l_reg, bf16x8& pa0, bf16x8& pa1, bf16x8& pa2, bf16x8& pa3) {
; #pragma unroll
;   for (int r = 0; r < 16; ++r) p1[r] = __builtin_amdgcn_exp2f(p1[r]);
;   float ps = 0;
; #pragma unroll
;   for (int r = 0; r < 16; ++r) ps += p0[r];
; #pragma unroll
;   for (int r = 0; r < 16; ++r) ps += p1[r];
;   { auto rr = __builtin_amdgcn_permlane32_swap(__float_as_uint(ps), __float_as_uint(ps), false, false);
;     ps = __uint_as_float(rr[0]) + __uint_as_float(rr[1]); }
;   l_reg = l_reg * alpha + ps;
;     ...
;   PK4(p0, 0, pa0); PK4(p0, 8, pa1); PK4(p1, 0, pa2); PK4(p1, 8, pa3);
; __device__ __forceinline__ void dattn_unit(const bf16* __restrict__ Qb, const bf16* __restrict__ Kh, const bf16* __restrict__ Vh, int nq, int kv_lo, int kv_hi, int NT, ...
;     ...
;       pv_one8<0>(o[0], vb, pa0, pa1, pa2, pa3); pv_one8<1>(o[1], vb, pa0, pa1, pa2, pa3); pv_one8<2>(o[2], vb, pa0, pa1, pa2, pa3); pv_one8<3>(o[3], vb, pa0, pa1, pa2, pa3);
;       pv_one8<4>(o[4], vb, pa0, pa1, pa2, pa3); pv_one8<5>(o[5], vb, pa0, pa1, pa2, pa3); pv_one8<6>(o[6], vb, pa0, pa1, pa2, pa3); pv_one8<7>(o[7], vb, pa0, pa1, pa2, pa3);
	v_mfma_f32_32x32x16_bf16 v[18:33], v[220:223], v[146:149], v[18:33]
	v_cvt_pk_bf16_f32 v133, v136, v137
	v_cvt_pk_bf16_f32 v134, v138, v139
	v_add_f32_e32 v204, v144, v204
	v_add_f32_e32 v204, v145, v204
	v_mfma_f32_32x32x16_bf16 v[18:33], v[224:227], v[150:153], v[18:33]
	v_cvt_pk_bf16_f32 v135, v140, v141
	v_cvt_pk_bf16_f32 v136, v142, v143
	v_cvt_pk_bf16_f32 v137, v144, v145
	v_add_f32_e32 v204, v250, v204
	ds_read_b64_tr_b16 v[146:147], v195 offset:8192
	ds_read_b64_tr_b16 v[148:149], v195 offset:10240
	ds_read_b64_tr_b16 v[150:151], v195 offset:12288
	ds_read_b64_tr_b16 v[152:153], v195 offset:14336
	s_waitcnt lgkmcnt(4)
	v_mfma_f32_32x32x16_bf16 v[2:17], v[220:223], v[154:157], v[2:17]
	v_mov_b32_e32 v206, v204
	v_permlane32_swap_b32_e32 v130, v132
	v_permlane32_swap_b32_e32 v131, v133
	v_mfma_f32_32x32x16_bf16 v[2:17], v[224:227], v[158:161], v[2:17]
	v_permlane32_swap_b32_e32 v134, v136
	v_permlane32_swap_b32_e32 v135, v137
	v_permlane32_swap_b32_e32 v204, v206
	v_add_f32_e32 v248, v204, v206
	v_fmac_f32_e32 v248, v247, v0
	v_mov_b32_e32 v247, v248
	ds_read_b64_tr_b16 v[154:155], v195 offset:8704
	ds_read_b64_tr_b16 v[156:157], v195 offset:10752
	ds_read_b64_tr_b16 v[158:159], v195 offset:12800
	ds_read_b64_tr_b16 v[160:161], v195 offset:14848
	s_waitcnt lgkmcnt(4)
	v_mfma_f32_32x32x16_bf16 v[114:129], v[130:133], v[146:149], v[114:129]
	v_mfma_f32_32x32x16_bf16 v[114:129], v[134:137], v[150:153], v[114:129]
	ds_read_b64_tr_b16 v[146:147], v195 offset:9216
	ds_read_b64_tr_b16 v[148:149], v195 offset:11264
	ds_read_b64_tr_b16 v[150:151], v195 offset:13312
	ds_read_b64_tr_b16 v[152:153], v195 offset:15360
	s_waitcnt lgkmcnt(4)
	v_mfma_f32_32x32x16_bf16 v[98:113], v[130:133], v[154:157], v[98:113]
	v_mfma_f32_32x32x16_bf16 v[98:113], v[134:137], v[158:161], v[98:113]
	ds_read_b64_tr_b16 v[154:155], v195 offset:9728
	ds_read_b64_tr_b16 v[156:157], v195 offset:11776
	ds_read_b64_tr_b16 v[158:159], v195 offset:13824
	ds_read_b64_tr_b16 v[160:161], v195 offset:15872
	s_waitcnt lgkmcnt(4)
	v_mfma_f32_32x32x16_bf16 v[82:97], v[130:133], v[146:149], v[82:97]
	v_mfma_f32_32x32x16_bf16 v[82:97], v[134:137], v[150:153], v[82:97]
	ds_read_b64_tr_b16 v[146:147], v195 offset:24576
	ds_read_b64_tr_b16 v[148:149], v195 offset:26624
	ds_read_b64_tr_b16 v[150:151], v195 offset:28672
	ds_read_b64_tr_b16 v[152:153], v195 offset:30720
	s_waitcnt lgkmcnt(4)
	v_mfma_f32_32x32x16_bf16 v[66:81], v[130:133], v[154:157], v[66:81]
	v_mfma_f32_32x32x16_bf16 v[66:81], v[134:137], v[158:161], v[66:81]
	ds_read_b64_tr_b16 v[154:155], v195 offset:25088
	ds_read_b64_tr_b16 v[156:157], v195 offset:27136
	ds_read_b64_tr_b16 v[158:159], v195 offset:29184
	ds_read_b64_tr_b16 v[160:161], v195 offset:31232
	s_waitcnt lgkmcnt(4)
	v_mfma_f32_32x32x16_bf16 v[50:65], v[130:133], v[146:149], v[50:65]
	v_mfma_f32_32x32x16_bf16 v[50:65], v[134:137], v[150:153], v[50:65]
	ds_read_b64_tr_b16 v[146:147], v195 offset:25600
	ds_read_b64_tr_b16 v[148:149], v195 offset:27648
	ds_read_b64_tr_b16 v[150:151], v195 offset:29696
	ds_read_b64_tr_b16 v[152:153], v195 offset:31744
	s_waitcnt lgkmcnt(4)
	v_mfma_f32_32x32x16_bf16 v[34:49], v[130:133], v[154:157], v[34:49]
	v_mfma_f32_32x32x16_bf16 v[34:49], v[134:137], v[158:161], v[34:49]
	ds_read_b64_tr_b16 v[154:155], v195 offset:26112
	ds_read_b64_tr_b16 v[156:157], v195 offset:28160
	ds_read_b64_tr_b16 v[158:159], v195 offset:30208
	ds_read_b64_tr_b16 v[160:161], v195 offset:32256
	s_waitcnt lgkmcnt(4)
	v_mfma_f32_32x32x16_bf16 v[18:33], v[130:133], v[146:149], v[18:33]
	v_mfma_f32_32x32x16_bf16 v[18:33], v[134:137], v[150:153], v[18:33]
	s_waitcnt lgkmcnt(0)
	v_mfma_f32_32x32x16_bf16 v[2:17], v[130:133], v[154:157], v[2:17]
	v_mfma_f32_32x32x16_bf16 v[2:17], v[134:137], v[158:161], v[2:17]

; __device__ __forceinline__ int v_rd_base(int lane) { return ((lane & 3) << 3) | (((lane >> 2) & 3) << 6) | (((lane >> 4) & 1) << 5) | (((lane >> 5) & 1) << 8); }
; __device__ __forceinline__ void partialSM(f32x16& p0, f32x16& p1, float& m_reg, float& mn, float& alpha, int rem, int hi) {
;     ...
;   float mnC = -mn * C;
; #pragma unroll
;   for (int r = 0; r < 16; ++r) p0[r] = fmaf(p0[r], C, mnC);
; #pragma unroll
;   for (int r = 0; r < 16; ++r) p1[r] = fmaf(p1[r], C, mnC);
; #pragma unroll
;   for (int r = 0; r < 16; ++r) p0[r] = __builtin_amdgcn_exp2f(p0[r]);
; __device__ __forceinline__ void qkt(f32x16& p0, f32x16& p1, const bf16* Ks, const bf16x8* qr, int r32, int hi) {
;   p0 = f32x16{}; p1 = f32x16{};
; #pragma unroll
;   for (int d0 = 0; d0 < 8; ++d0) { int cb = (d0 * 16 + hi * 8) * 2;
;     bf16x8 b0 = *reinterpret_cast<const bf16x8*>((const char*)Ks + KSWZ(r32, cb));
;     bf16x8 b1 = *reinterpret_cast<const bf16x8*>((const char*)Ks + KSWZ(32 + r32, cb));
;     p0 = __builtin_amdgcn_mfma_f32_32x32x16_bf16(b0, qr[d0], p0, 0, 0, 0);
;     p1 = __builtin_amdgcn_mfma_f32_32x32x16_bf16(b1, qr[d0], p1, 0, 0, 0); }
; __device__ __forceinline__ void dattn_unit(const bf16* __restrict__ Qb, const bf16* __restrict__ Kh, const bf16* __restrict__ Vh, int nq, int kv_lo, int kv_hi, int NT, ...
;     ...
;     asm volatile("s_waitcnt vmcnt(0)" ::: "memory");
;     __builtin_amdgcn_s_barrier();
;     if (t + 1 < NT) DMA_TILE(t + 1, (t + 1) & 1);
;     const int rem = kvalid - 64 * t;
;     if (active && rem > 0) {
;       const bf16* Ks = (const bf16*)(lds + (t & 1) * 65536 + br * 16384);
;       const int vb = (int)(uintptr_t)(lds + (t & 1) * 65536 + 32768) + v_rd_base(lane);
;       f32x16 p0, p1; float mn, al; bf16x8 pa0, pa1, pa2, pa3;
;       p0 = f32x16{}; p1 = f32x16{};
; #pragma unroll
;       for (int d0 = 0; d0 < 8; ++d0) { const int cb = (d0 * 16 + hi * 8) * 2;
;         const bf16x8 b0 = *reinterpret_cast<const bf16x8*>((const char*)Ks + KSWZ(r32, cb));
;         const bf16x8 b1 = *reinterpret_cast<const bf16x8*>((const char*)Ks + KSWZ(32 + r32, cb));
;         p0 = __builtin_amdgcn_mfma_f32_32x32x16_bf16(b0, qr[d0], p0, 0, 0, 0);
;         p1 = __builtin_amdgcn_mfma_f32_32x32x16_bf16(b1, qr[d0], p1, 0, 0, 0);
;         }
;       partialSM(p0, p1, m_reg, mn, al, rem, hi);
.LBB0_939:
	s_waitcnt vmcnt(0)
	s_add_i32 s28, s28, 1
	s_barrier
	s_cmp_gt_i32 s25, 0
	s_cselect_b64 s[4:5], -1, 0
	s_and_b64 s[4:5], s[12:13], s[4:5]
	s_cbranch_scc0 .Latt_nocompute
	s_cmp_ge_u32 s28, s23
	s_cbranch_scc1 .Latt_qk_nodma
	s_and_b32 s4, s27, 0x10000
	s_add_i32 s29, s4, 0
	s_add_i32 s4, s29, s26
	s_add_i32 s32, s27, 0x10000
	s_and_b32 s32, s32, 0x10000
	s_add_i32 s32, s24, s32
	v_add3_u32 v0, s4, v238, v236
	ds_read_b128 v[194:197], v0
	v_add3_u32 v0, s4, v239, v236
	ds_read_b128 v[198:201], v0
	v_add3_u32 v0, s4, v240, v236
	ds_read_b128 v[202:205], v0
	v_add3_u32 v0, s4, v241, v236
	ds_read_b128 v[206:209], v0
	v_mul_f32_e32 v249, 0xbe0293ee, v246
	s_waitcnt lgkmcnt(3)
	v_mfma_f32_32x32x16_bf16 v[146:161], v[194:197], v[162:165], 0
	v_add3_u32 v0, s4, v242, v236
	ds_read_b128 v[194:197], v0
	s_mov_b32 m0, s32
	s_nop 0
	global_load_lds_dwordx4 v212, s[14:15]
	s_waitcnt lgkmcnt(3)
	v_mfma_f32_32x32x16_bf16 v[146:161], v[198:201], v[166:169], v[146:161]
	v_add3_u32 v0, s4, v243, v236
	ds_read_b128 v[198:201], v0
	s_add_i32 m0, s32, 0x400
	s_nop 0
	global_load_lds_dwordx4 v213, s[14:15]
	s_waitcnt lgkmcnt(3)
	v_mfma_f32_32x32x16_bf16 v[146:161], v[202:205], v[170:173], v[146:161]
	v_add3_u32 v0, s4, v244, v236
	ds_read_b128 v[202:205], v0
	s_add_i32 m0, s32, 0x800
	s_nop 0
	global_load_lds_dwordx4 v214, s[14:15]
	s_waitcnt lgkmcnt(3)
	v_mfma_f32_32x32x16_bf16 v[146:161], v[206:209], v[174:177], v[146:161]
	v_add3_u32 v0, s4, v245, v236
	ds_read_b128 v[206:209], v0
	s_add_i32 m0, s32, 0xc00
	s_nop 0
	global_load_lds_dwordx4 v215, s[14:15]
	s_waitcnt lgkmcnt(3)
	v_mfma_f32_32x32x16_bf16 v[146:161], v[194:197], v[178:181], v[146:161]
	v_add3_u32 v0, s4, v238, v236
	ds_read_b128 v[194:197], v0 offset:8192
	s_add_i32 m0, s32, 0x1000
	s_nop 0
	global_load_lds_dwordx4 v216, s[14:15]
	s_waitcnt lgkmcnt(3)
	v_mfma_f32_32x32x16_bf16 v[146:161], v[198:201], v[182:185], v[146:161]
	v_add3_u32 v0, s4, v239, v236
	ds_read_b128 v[198:201], v0 offset:8192
	s_add_i32 m0, s32, 0x1400
	s_nop 0
	global_load_lds_dwordx4 v217, s[14:15]
	s_waitcnt lgkmcnt(3)
	v_mfma_f32_32x32x16_bf16 v[146:161], v[202:205], v[186:189], v[146:161]
	v_add3_u32 v0, s4, v240, v236
	ds_read_b128 v[202:205], v0 offset:8192
	s_add_i32 m0, s32, 0x1800
	s_nop 0
	global_load_lds_dwordx4 v218, s[14:15]
	s_waitcnt lgkmcnt(3)
	v_mfma_f32_32x32x16_bf16 v[146:161], v[206:209], v[190:193], v[146:161]
	v_add3_u32 v0, s4, v241, v236
	ds_read_b128 v[206:209], v0 offset:8192
	s_add_i32 m0, s32, 0x1c00
	s_nop 0
	global_load_lds_dwordx4 v219, s[14:15]
	s_waitcnt lgkmcnt(3)
	v_mfma_f32_32x32x16_bf16 v[130:145], v[194:197], v[162:165], 0
	v_add3_u32 v0, s4, v242, v236
	ds_read_b128 v[194:197], v0 offset:8192
	s_waitcnt lgkmcnt(3)
	v_mfma_f32_32x32x16_bf16 v[130:145], v[198:201], v[166:169], v[130:145]
	v_add3_u32 v0, s4, v243, v236
	ds_read_b128 v[198:201], v0 offset:8192
	s_nop 7
	s_nop 3
	v_fmamk_f32 v251, v146, 0x3e0293ee, v249
	v_fmamk_f32 v255, v147, 0x3e0293ee, v249
	v_exp_f32_e32 v251, v251
	v_exp_f32_e32 v255, v255
	v_max3_f32 v248, v146, v147, v148
	v_add_f32_e32 v250, v251, v255
	v_cvt_pk_bf16_f32 v220, v251, v255
	v_fmamk_f32 v251, v148, 0x3e0293ee, v249
	s_waitcnt lgkmcnt(3)
	v_mfma_f32_32x32x16_bf16 v[130:145], v[202:205], v[170:173], v[130:145]
	v_add3_u32 v0, s4, v244, v236
	ds_read_b128 v[202:205], v0 offset:8192
	v_fmamk_f32 v255, v149, 0x3e0293ee, v249
	v_exp_f32_e32 v251, v251
	v_exp_f32_e32 v255, v255
	v_max3_f32 v248, v248, v149, v150
	v_add_f32_e32 v250, v251, v250
	v_add_f32_e32 v250, v255, v250
	v_cvt_pk_bf16_f32 v221, v251, v255
	v_fmamk_f32 v251, v150, 0x3e0293ee, v249
	v_fmamk_f32 v255, v151, 0x3e0293ee, v249
	v_exp_f32_e32 v251, v251
	s_waitcnt lgkmcnt(3)
	v_mfma_f32_32x32x16_bf16 v[130:145], v[206:209], v[174:177], v[130:145]
	v_add3_u32 v0, s4, v245, v236
	ds_read_b128 v[206:209], v0 offset:8192
	v_exp_f32_e32 v255, v255
	v_max3_f32 v248, v248, v151, v152
	v_add_f32_e32 v250, v251, v250
	v_add_f32_e32 v250, v255, v250
	v_cvt_pk_bf16_f32 v222, v251, v255
	v_fmamk_f32 v251, v152, 0x3e0293ee, v249
	v_fmamk_f32 v255, v153, 0x3e0293ee, v249
	v_exp_f32_e32 v251, v251
	v_exp_f32_e32 v255, v255
	v_max3_f32 v248, v248, v153, v154
	s_waitcnt lgkmcnt(3)
	v_mfma_f32_32x32x16_bf16 v[130:145], v[194:197], v[178:181], v[130:145]
	v_add_f32_e32 v250, v251, v250
	v_add_f32_e32 v250, v255, v250
	v_cvt_pk_bf16_f32 v223, v251, v255
	v_fmamk_f32 v251, v154, 0x3e0293ee, v249
	v_fmamk_f32 v255, v155, 0x3e0293ee, v249
	v_exp_f32_e32 v251, v251
	v_exp_f32_e32 v255, v255
	v_max3_f32 v248, v248, v155, v156
	v_add_f32_e32 v250, v251, v250
	v_add_f32_e32 v250, v255, v250
	s_waitcnt lgkmcnt(2)
	v_mfma_f32_32x32x16_bf16 v[130:145], v[198:201], v[182:185], v[130:145]
	v_cvt_pk_bf16_f32 v224, v251, v255
	v_fmamk_f32 v251, v156, 0x3e0293ee, v249
	v_fmamk_f32 v255, v157, 0x3e0293ee, v249
	v_exp_f32_e32 v251, v251
	v_exp_f32_e32 v255, v255
	v_max3_f32 v248, v248, v157, v158
	v_add_f32_e32 v250, v251, v250
	v_add_f32_e32 v250, v255, v250
	v_cvt_pk_bf16_f32 v225, v251, v255
	v_fmamk_f32 v251, v158, 0x3e0293ee, v249
	s_waitcnt lgkmcnt(1)
	v_mfma_f32_32x32x16_bf16 v[130:145], v[202:205], v[186:189], v[130:145]
	v_fmamk_f32 v255, v159, 0x3e0293ee, v249
	v_exp_f32_e32 v251, v251
	v_exp_f32_e32 v255, v255
	v_max3_f32 v248, v248, v159, v160
	v_add_f32_e32 v250, v251, v250
	v_add_f32_e32 v250, v255, v250
	v_cvt_pk_bf16_f32 v226, v251, v255
	v_fmamk_f32 v251, v160, 0x3e0293ee, v249
	v_fmamk_f32 v255, v161, 0x3e0293ee, v249
	v_exp_f32_e32 v251, v251
	s_waitcnt lgkmcnt(0)
	v_mfma_f32_32x32x16_bf16 v[130:145], v[206:209], v[190:193], v[130:145]
	v_exp_f32_e32 v255, v255
	v_max_f32_e32 v248, v248, v161
	v_add_f32_e32 v250, v251, v250
	v_add_f32_e32 v250, v255, v250
	v_cvt_pk_bf16_f32 v227, v251, v255
	v_permlane32_swap_b32_e32 v220, v222
	v_permlane32_swap_b32_e32 v221, v223
	v_permlane32_swap_b32_e32 v224, v226
	v_permlane32_swap_b32_e32 v225, v227
	s_branch .Latt_qk_done
; __device__ __forceinline__ void partialSM(f32x16& p0, f32x16& p1, float& m_reg, float& mn, float& alpha, int rem, int hi) {
;     ...
;   float mnC = -mn * C;
; #pragma unroll
;   for (int r = 0; r < 16; ++r) p0[r] = fmaf(p0[r], C, mnC);
; #pragma unroll
;   for (int r = 0; r < 16; ++r) p1[r] = fmaf(p1[r], C, mnC);
; #pragma unroll
;   for (int r = 0; r < 16; ++r) p0[r] = __builtin_amdgcn_exp2f(p0[r]);
; __device__ __forceinline__ void dattn_unit(const bf16* __restrict__ Qb, const bf16* __restrict__ Kh, const bf16* __restrict__ Vh, int nq, int kv_lo, int kv_hi, int NT, ...
;     ...
;       p0 = f32x16{}; p1 = f32x16{};
; #pragma unroll
;       for (int d0 = 0; d0 < 8; ++d0) { const int cb = (d0 * 16 + hi * 8) * 2;
;         const bf16x8 b0 = *reinterpret_cast<const bf16x8*>((const char*)Ks + KSWZ(r32, cb));
;         const bf16x8 b1 = *reinterpret_cast<const bf16x8*>((const char*)Ks + KSWZ(32 + r32, cb));
;         p0 = __builtin_amdgcn_mfma_f32_32x32x16_bf16(b0, qr[d0], p0, 0, 0, 0);
;         p1 = __builtin_amdgcn_mfma_f32_32x32x16_bf16(b1, qr[d0], p1, 0, 0, 0);
;         }
;       partialSM(p0, p1, m_reg, mn, al, rem, hi);
.Latt_qk_nodma:
	s_and_b32 s4, s27, 0x10000
	s_add_i32 s29, s4, 0
	s_add_i32 s4, s29, s26
	v_add3_u32 v0, s4, v238, v236
	ds_read_b128 v[194:197], v0
	v_add3_u32 v0, s4, v239, v236
	ds_read_b128 v[198:201], v0
	v_add3_u32 v0, s4, v240, v236
	ds_read_b128 v[202:205], v0
	v_add3_u32 v0, s4, v241, v236
	ds_read_b128 v[206:209], v0
	v_mul_f32_e32 v249, 0xbe0293ee, v246
	s_waitcnt lgkmcnt(3)
	v_mfma_f32_32x32x16_bf16 v[146:161], v[194:197], v[162:165], 0
	v_add3_u32 v0, s4, v242, v236
	ds_read_b128 v[194:197], v0
	s_waitcnt lgkmcnt(3)
	v_mfma_f32_32x32x16_bf16 v[146:161], v[198:201], v[166:169], v[146:161]
	v_add3_u32 v0, s4, v243, v236
	ds_read_b128 v[198:201], v0
	s_waitcnt lgkmcnt(3)
	v_mfma_f32_32x32x16_bf16 v[146:161], v[202:205], v[170:173], v[146:161]
	v_add3_u32 v0, s4, v244, v236
	ds_read_b128 v[202:205], v0
	s_waitcnt lgkmcnt(3)
	v_mfma_f32_32x32x16_bf16 v[146:161], v[206:209], v[174:177], v[146:161]
	v_add3_u32 v0, s4, v245, v236
	ds_read_b128 v[206:209], v0
	s_waitcnt lgkmcnt(3)
	v_mfma_f32_32x32x16_bf16 v[146:161], v[194:197], v[178:181], v[146:161]
	v_add3_u32 v0, s4, v238, v236
	ds_read_b128 v[194:197], v0 offset:8192
	s_waitcnt lgkmcnt(3)
	v_mfma_f32_32x32x16_bf16 v[146:161], v[198:201], v[182:185], v[146:161]
	v_add3_u32 v0, s4, v239, v236
	ds_read_b128 v[198:201], v0 offset:8192
	s_waitcnt lgkmcnt(3)
	v_mfma_f32_32x32x16_bf16 v[146:161], v[202:205], v[186:189], v[146:161]
	v_add3_u32 v0, s4, v240, v236
	ds_read_b128 v[202:205], v0 offset:8192
	s_waitcnt lgkmcnt(3)
	v_mfma_f32_32x32x16_bf16 v[146:161], v[206:209], v[190:193], v[146:161]
	v_add3_u32 v0, s4, v241, v236
	ds_read_b128 v[206:209], v0 offset:8192
	s_waitcnt lgkmcnt(3)
	v_mfma_f32_32x32x16_bf16 v[130:145], v[194:197], v[162:165], 0
	v_add3_u32 v0, s4, v242, v236
	ds_read_b128 v[194:197], v0 offset:8192
	s_waitcnt lgkmcnt(3)
	v_mfma_f32_32x32x16_bf16 v[130:145], v[198:201], v[166:169], v[130:145]
	v_add3_u32 v0, s4, v243, v236
	ds_read_b128 v[198:201], v0 offset:8192
	s_nop 7
	s_nop 3
	v_fmamk_f32 v251, v146, 0x3e0293ee, v249
	v_fmamk_f32 v255, v147, 0x3e0293ee, v249
	v_exp_f32_e32 v251, v251
	v_exp_f32_e32 v255, v255
	v_max3_f32 v248, v146, v147, v148
	v_add_f32_e32 v250, v251, v255
	v_cvt_pk_bf16_f32 v220, v251, v255
	v_fmamk_f32 v251, v148, 0x3e0293ee, v249
	s_waitcnt lgkmcnt(3)
	v_mfma_f32_32x32x16_bf16 v[130:145], v[202:205], v[170:173], v[130:145]
	v_add3_u32 v0, s4, v244, v236
	ds_read_b128 v[202:205], v0 offset:8192
	v_fmamk_f32 v255, v149, 0x3e0293ee, v249
	v_exp_f32_e32 v251, v251
	v_exp_f32_e32 v255, v255
	v_max3_f32 v248, v248, v149, v150
	v_add_f32_e32 v250, v251, v250
	v_add_f32_e32 v250, v255, v250
	v_cvt_pk_bf16_f32 v221, v251, v255
	v_fmamk_f32 v251, v150, 0x3e0293ee, v249
	v_fmamk_f32 v255, v151, 0x3e0293ee, v249
	v_exp_f32_e32 v251, v251
	s_waitcnt lgkmcnt(3)
	v_mfma_f32_32x32x16_bf16 v[130:145], v[206:209], v[174:177], v[130:145]
	v_add3_u32 v0, s4, v245, v236
	ds_read_b128 v[206:209], v0 offset:8192
	v_exp_f32_e32 v255, v255
	v_max3_f32 v248, v248, v151, v152
	v_add_f32_e32 v250, v251, v250
	v_add_f32_e32 v250, v255, v250
	v_cvt_pk_bf16_f32 v222, v251, v255
	v_fmamk_f32 v251, v152, 0x3e0293ee, v249
	v_fmamk_f32 v255, v153, 0x3e0293ee, v249
	v_exp_f32_e32 v251, v251
	v_exp_f32_e32 v255, v255
	v_max3_f32 v248, v248, v153, v154
	s_waitcnt lgkmcnt(3)
	v_mfma_f32_32x32x16_bf16 v[130:145], v[194:197], v[178:181], v[130:145]
	v_add_f32_e32 v250, v251, v250
	v_add_f32_e32 v250, v255, v250
	v_cvt_pk_bf16_f32 v223, v251, v255
	v_fmamk_f32 v251, v154, 0x3e0293ee, v249
	v_fmamk_f32 v255, v155, 0x3e0293ee, v249
	v_exp_f32_e32 v251, v251
	v_exp_f32_e32 v255, v255
	v_max3_f32 v248, v248, v155, v156
	v_add_f32_e32 v250, v251, v250
	v_add_f32_e32 v250, v255, v250
	s_waitcnt lgkmcnt(2)
	v_mfma_f32_32x32x16_bf16 v[130:145], v[198:201], v[182:185], v[130:145]
	v_cvt_pk_bf16_f32 v224, v251, v255
	v_fmamk_f32 v251, v156, 0x3e0293ee, v249
	v_fmamk_f32 v255, v157, 0x3e0293ee, v249
	v_exp_f32_e32 v251, v251
	v_exp_f32_e32 v255, v255
	v_max3_f32 v248, v248, v157, v158
	v_add_f32_e32 v250, v251, v250
	v_add_f32_e32 v250, v255, v250
	v_cvt_pk_bf16_f32 v225, v251, v255
	v_fmamk_f32 v251, v158, 0x3e0293ee, v249
	s_waitcnt lgkmcnt(1)
	v_mfma_f32_32x32x16_bf16 v[130:145], v[202:205], v[186:189], v[130:145]
	v_fmamk_f32 v255, v159, 0x3e0293ee, v249
	v_exp_f32_e32 v251, v251
	v_exp_f32_e32 v255, v255
	v_max3_f32 v248, v248, v159, v160
	v_add_f32_e32 v250, v251, v250
	v_add_f32_e32 v250, v255, v250
	v_cvt_pk_bf16_f32 v226, v251, v255
	v_fmamk_f32 v251, v160, 0x3e0293ee, v249
	v_fmamk_f32 v255, v161, 0x3e0293ee, v249
	v_exp_f32_e32 v251, v251
	s_waitcnt lgkmcnt(0)
	v_mfma_f32_32x32x16_bf16 v[130:145], v[206:209], v[190:193], v[130:145]
	v_exp_f32_e32 v255, v255
	v_max_f32_e32 v248, v248, v161
	v_add_f32_e32 v250, v251, v250
	v_add_f32_e32 v250, v255, v250
	v_cvt_pk_bf16_f32 v227, v251, v255
	v_permlane32_swap_b32_e32 v220, v222
	v_permlane32_swap_b32_e32 v221, v223
	v_permlane32_swap_b32_e32 v224, v226
	v_permlane32_swap_b32_e32 v225, v227

; __device__ __forceinline__ void partialSM(f32x16& p0, f32x16& p1, float& m_reg, float& mn, float& alpha, int rem, int hi) {
;   constexpr float C = SCALE * 1.4426950408889634f;
;   if (rem < 64) {
; #pragma unroll
;     for (int r = 0; r < 16; ++r) { if (8 * (r >> 2) >= rem) p0[r] = -1e30f; if (32 + 8 * (r >> 2) >= rem) p1[r] = -1e30f; }
;   }
;   float pmax = p0[0];
; #pragma unroll
;   for (int r = 1; r < 16; ++r) pmax = fmaxf(pmax, p0[r]);
; #pragma unroll
;   for (int r = 0; r < 16; ++r) pmax = fmaxf(pmax, p1[r]);
;   { auto rr = __builtin_amdgcn_permlane32_swap(__float_as_uint(pmax), __float_as_uint(pmax), false, false);
;     pmax = fmaxf(__uint_as_float(rr[0]), __uint_as_float(rr[1])); }
;   if (__builtin_expect(__all(pmax - m_reg <= THR / SCALE), 1)) { mn = m_reg; alpha = 1.f; }
;   else { mn = fmaxf(m_reg, pmax); alpha = __builtin_amdgcn_exp2f((m_reg - mn) * C); m_reg = mn; }
;   float mnC = -mn * C;
; #pragma unroll
;   for (int r = 0; r < 16; ++r) p0[r] = fmaf(p0[r], C, mnC);
; #pragma unroll
;   for (int r = 0; r < 16; ++r) p1[r] = fmaf(p1[r], C, mnC);
; #pragma unroll
;   for (int r = 0; r < 16; ++r) p0[r] = __builtin_amdgcn_exp2f(p0[r]);
; }
.LBB0_945:
	s_or_b64 s[4:5], vcc, s[18:19]
	v_cndmask_b32_e64 v157, v228, v157, s[4:5]
	v_cndmask_b32_e64 v156, v228, v156, s[4:5]
	v_cndmask_b32_e64 v155, v228, v155, s[4:5]
	v_cndmask_b32_e64 v154, v228, v154, s[4:5]
	s_or_b64 s[4:5], s[4:5], s[16:17]
	v_cndmask_b32_e64 v153, v228, v153, s[4:5]
	s_or_b64 s[4:5], s[4:5], vcc
	v_cndmask_b32_e64 v152, v228, v152, s[4:5]
	v_cndmask_b32_e64 v151, v228, v151, s[4:5]
	v_cndmask_b32_e64 v150, v228, v150, s[4:5]
	v_cndmask_b32_e32 v161, v228, v161, vcc
	v_cndmask_b32_e32 v160, v228, v160, vcc
	v_cndmask_b32_e32 v159, v228, v159, vcc
	v_cndmask_b32_e32 v158, v228, v158, vcc
	v_max3_f32 v248, v146, v147, v148
	v_max3_f32 v248, v248, v149, v150
	v_max3_f32 v248, v248, v151, v152
	v_max3_f32 v248, v248, v153, v154
	v_max3_f32 v248, v248, v155, v156
	v_max3_f32 v248, v248, v157, v158
	v_max3_f32 v248, v248, v159, v160
	v_max_f32_e32 v248, v248, v161
.LBB0_946:
	s_nop 7
	v_max3_f32 v0, v248, v130, v131
	v_max3_f32 v0, v0, v132, v133
	v_max3_f32 v0, v0, v134, v135
	v_max3_f32 v0, v0, v136, v137
	v_max3_f32 v0, v0, v138, v139
	v_max3_f32 v0, v0, v140, v141
	v_max3_f32 v0, v0, v142, v143
	v_max3_f32 v0, v0, v144, v145
	v_mov_b32_e32 v194, v0
	s_nop 1
	v_permlane32_swap_b32_e32 v0, v194
	v_max_f32_e32 v194, v194, v194
	v_max_f32_e32 v0, v0, v0
	v_max_f32_e32 v0, v0, v194
	v_sub_f32_e32 v194, v0, v246
	s_mov_b32 s4, 0x42b504f3
	v_cmp_ge_f32_e32 vcc, s4, v194
	v_max_f32_e32 v194, v246, v246
	v_max_f32_e32 v248, v194, v0
	v_sub_f32_e32 v0, v246, v248
	v_mul_f32_e32 v0, 0x3e0293ee, v0
	v_exp_f32_e32 v0, v0
	s_cmp_eq_u64 vcc, exec
	s_cselect_b64 s[4:5], -1, 0
	v_cndmask_b32_e64 v0, v0, 1.0, s[4:5]
	v_cmp_gt_f32_e32 vcc, 1.0, v0
	s_cbranch_vccz .LBB0_937
	s_and_saveexec_b64 s[6:7], s[0:1]
	s_cbranch_execz .LBB0_936
	ds_write_b32 v234, v0 offset:128
	s_branch .LBB0_936
.Latt_s1_redo:
	v_mul_f32_e32 v249, 0xbe0293ee, v246
	v_fmamk_f32 v146, v146, 0x3e0293ee, v249
	v_fmamk_f32 v147, v147, 0x3e0293ee, v249
	v_fmamk_f32 v148, v148, 0x3e0293ee, v249
	v_fmamk_f32 v149, v149, 0x3e0293ee, v249
	v_fmamk_f32 v150, v150, 0x3e0293ee, v249
	v_fmamk_f32 v151, v151, 0x3e0293ee, v249
	v_fmamk_f32 v152, v152, 0x3e0293ee, v249
	v_fmamk_f32 v153, v153, 0x3e0293ee, v249
	v_fmamk_f32 v154, v154, 0x3e0293ee, v249
	v_fmamk_f32 v155, v155, 0x3e0293ee, v249
	v_fmamk_f32 v156, v156, 0x3e0293ee, v249
	v_fmamk_f32 v157, v157, 0x3e0293ee, v249
	v_fmamk_f32 v158, v158, 0x3e0293ee, v249
	v_fmamk_f32 v159, v159, 0x3e0293ee, v249
	v_fmamk_f32 v160, v160, 0x3e0293ee, v249
	v_fmamk_f32 v161, v161, 0x3e0293ee, v249
	v_exp_f32_e32 v146, v146
	v_exp_f32_e32 v147, v147
	v_exp_f32_e32 v148, v148
	v_exp_f32_e32 v149, v149
	v_exp_f32_e32 v150, v150
	v_exp_f32_e32 v151, v151
	v_exp_f32_e32 v152, v152
	v_exp_f32_e32 v153, v153
	v_exp_f32_e32 v154, v154
	v_exp_f32_e32 v155, v155
	v_exp_f32_e32 v156, v156
	v_exp_f32_e32 v157, v157
	v_exp_f32_e32 v158, v158
	v_exp_f32_e32 v159, v159
	v_exp_f32_e32 v160, v160
	v_exp_f32_e32 v161, v161
	v_add_f32_e32 v250, v146, v147
	v_add_f32_e32 v250, v148, v250
	v_add_f32_e32 v250, v149, v250
	v_add_f32_e32 v250, v150, v250
	v_add_f32_e32 v250, v151, v250
	v_add_f32_e32 v250, v152, v250
	v_add_f32_e32 v250, v153, v250
	v_add_f32_e32 v250, v154, v250
	v_add_f32_e32 v250, v155, v250
	v_add_f32_e32 v250, v156, v250
	v_add_f32_e32 v250, v157, v250
	v_add_f32_e32 v250, v158, v250
	v_add_f32_e32 v250, v159, v250
	v_add_f32_e32 v250, v160, v250
	v_add_f32_e32 v250, v161, v250
	v_cvt_pk_bf16_f32 v220, v146, v147
	v_cvt_pk_bf16_f32 v221, v148, v149
	v_cvt_pk_bf16_f32 v222, v150, v151
	v_cvt_pk_bf16_f32 v223, v152, v153
	v_cvt_pk_bf16_f32 v224, v154, v155
	v_cvt_pk_bf16_f32 v225, v156, v157
	v_cvt_pk_bf16_f32 v226, v158, v159
	v_cvt_pk_bf16_f32 v227, v160, v161
	s_nop 1
	v_permlane32_swap_b32_e32 v220, v222
	v_permlane32_swap_b32_e32 v221, v223
	v_permlane32_swap_b32_e32 v224, v226
	v_permlane32_swap_b32_e32 v225, v227
	s_branch .Latt_pv
.Latt_nocompute:
	s_cmp_ge_u32 s28, s23
	s_cbranch_scc1 .LBB0_938
	s_add_i32 s32, s27, 0x10000
	s_and_b32 s32, s32, 0x10000
	s_add_i32 s32, s24, s32
	s_mov_b32 m0, s32
	s_nop 0
	global_load_lds_dwordx4 v212, s[14:15]
	s_add_i32 m0, s32, 0x400
	s_nop 0
	global_load_lds_dwordx4 v213, s[14:15]
	s_add_i32 m0, s32, 0x800
	s_nop 0
	global_load_lds_dwordx4 v214, s[14:15]
	s_add_i32 m0, s32, 0xc00
	s_nop 0
	global_load_lds_dwordx4 v215, s[14:15]
	s_add_i32 m0, s32, 0x1000
	s_nop 0
	global_load_lds_dwordx4 v216, s[14:15]
	s_add_i32 m0, s32, 0x1400
	s_nop 0
	global_load_lds_dwordx4 v217, s[14:15]
	s_add_i32 m0, s32, 0x1800
	s_nop 0
	global_load_lds_dwordx4 v218, s[14:15]
	s_add_i32 m0, s32, 0x1c00
	s_nop 0
	global_load_lds_dwordx4 v219, s[14:15]
	s_branch .LBB0_938

; __global__ void __launch_bounds__(NWAVES * 64, 2) fwd_kernel(Args args) {
	.amdhsa_kernel _Z10fwd_kernel4Args
		.amdhsa_group_segment_fixed_size 0
		.amdhsa_private_segment_fixed_size 0
		.amdhsa_kernarg_size 472
		.amdhsa_user_sgpr_count 2
		.amdhsa_user_sgpr_dispatch_ptr 0
		.amdhsa_user_sgpr_queue_ptr 0
		.amdhsa_user_sgpr_kernarg_segment_ptr 1
		.amdhsa_user_sgpr_dispatch_id 0
		.amdhsa_user_sgpr_kernarg_preload_length 0
		.amdhsa_user_sgpr_kernarg_preload_offset 0
		.amdhsa_user_sgpr_private_segment_size 0
		.amdhsa_uses_dynamic_stack 0
		.amdhsa_enable_private_segment 0
		.amdhsa_system_sgpr_workgroup_id_x 1
		.amdhsa_system_sgpr_workgroup_id_y 0
		.amdhsa_system_sgpr_workgroup_id_z 0
		.amdhsa_system_sgpr_workgroup_info 0
		.amdhsa_system_vgpr_workitem_id 0
		.amdhsa_next_free_vgpr 256
		.amdhsa_next_free_sgpr 98
		.amdhsa_accum_offset 256
		.amdhsa_reserve_vcc 1
		.amdhsa_float_round_mode_32 0
		.amdhsa_float_round_mode_16_64 0
		.amdhsa_float_denorm_mode_32 3
		.amdhsa_float_denorm_mode_16_64 3
		.amdhsa_dx10_clamp 1
		.amdhsa_ieee_mode 1
		.amdhsa_fp16_overflow 0
		.amdhsa_tg_split 0
		.amdhsa_exception_fp_ieee_invalid_op 0
		.amdhsa_exception_fp_denorm_src 0
		.amdhsa_exception_fp_ieee_div_zero 0
		.amdhsa_exception_fp_ieee_overflow 0
		.amdhsa_exception_fp_ieee_underflow 0
		.amdhsa_exception_fp_ieee_inexact 0
		.amdhsa_exception_int_div_zero 0
	.end_amdhsa_kernel

; __global__ void __launch_bounds__(NWAVES * 64, 2) fwd_kernel(Args args) {
;     extern __shared__ __attribute__((aligned(16))) unsigned char lds[];
amdhsa.kernels:
  - .agpr_count:     0
    .args:
      - .offset:         0
        .size:           216
        .value_kind:     by_value
      - .offset:         216
        .size:           4
        .value_kind:     hidden_block_count_x
      - .offset:         220
        .size:           4
        .value_kind:     hidden_block_count_y
      - .offset:         224
        .size:           4
        .value_kind:     hidden_block_count_z
      - .offset:         228
        .size:           2
        .value_kind:     hidden_group_size_x
      - .offset:         230
        .size:           2
        .value_kind:     hidden_group_size_y
      - .offset:         232
        .size:           2
        .value_kind:     hidden_group_size_z
      - .offset:         234
        .size:           2
        .value_kind:     hidden_remainder_x
      - .offset:         236
        .size:           2
        .value_kind:     hidden_remainder_y
      - .offset:         238
        .size:           2
        .value_kind:     hidden_remainder_z
      - .offset:         256
        .size:           8
        .value_kind:     hidden_global_offset_x
      - .offset:         264
        .size:           8
        .value_kind:     hidden_global_offset_y
      - .offset:         272
        .size:           8
        .value_kind:     hidden_global_offset_z
      - .offset:         280
        .size:           2
        .value_kind:     hidden_grid_dims
      - .offset:         336
        .size:           4
        .value_kind:     hidden_dynamic_lds_size
    .group_segment_fixed_size: 0
    .kernarg_segment_align: 8
    .kernarg_segment_size: 472
    .language:       OpenCL C
    .language_version:
      - 2
      - 0
    .max_flat_workgroup_size: 512
    .name:           _Z10fwd_kernel4Args
    .private_segment_fixed_size: 0
    .sgpr_count:     104
    .sgpr_spill_count: 197
    .symbol:         _Z10fwd_kernel4Args.kd
    .uniform_work_group_size: 1
    .uses_dynamic_stack: false
    .vgpr_count:     256
    .vgpr_spill_count: 0
    .wavefront_size: 64
